# grid barrier waiters poll the top-level arrival counter against (generation+1)*n_xcd instead of the generation word (one more round trip off the barrier critical path)
# speedup vs baseline: 1.0000x; 1.0000x over previous
.LBB0_40:
	s_or_b64 exec, exec, s[22:23]
	v_cvt_f32_u32_e32 v5, v3
	s_waitcnt vmcnt(0)
	v_readfirstlane_b32 s2, v4
	v_sub_u32_e32 v4, 0, v3
	v_rcp_iflag_f32_e32 v5, v5
	v_add_u32_e32 v6, s2, v2
	v_mul_f32_e32 v5, 0x4f7ffffe, v5
	v_cvt_u32_f32_e32 v5, v5
	v_mul_lo_u32 v2, v4, v5
	v_mul_hi_u32 v2, v5, v2
	v_add_u32_e32 v2, v5, v2
	v_mul_hi_u32 v2, v6, v2
	v_mul_lo_u32 v4, v2, v3
	v_sub_u32_e32 v4, v6, v4
	v_add_u32_e32 v5, 1, v2
	v_sub_u32_e32 v7, v4, v3
	v_cmp_ge_u32_e32 vcc, v4, v3
	s_nop 1
	v_cndmask_b32_e32 v2, v2, v5, vcc
	v_cndmask_b32_e32 v4, v4, v7, vcc
	v_add_u32_e32 v5, 1, v2
	v_cmp_ge_u32_e32 vcc, v4, v3
	v_add_u32_e32 v4, 1, v6
	s_nop 0
	v_cndmask_b32_e32 v2, v2, v5, vcc
	v_mul_lo_u32 v5, v3, v2
	v_add_u32_e32 v3, v5, v3
	v_cmp_ne_u32_e32 vcc, v4, v3
	s_and_saveexec_b64 s[22:23], vcc
	s_xor_b64 s[22:23], exec, s[22:23]
	s_cbranch_execz .LBB0_54
	v_readlane_b32 s4, v247, 48
	v_readlane_b32 s5, v247, 49
	s_waitcnt lgkmcnt(0)
	v_add_u32_e32 v19, 1, v2
	v_mul_lo_u32 v19, v19, v1
	s_nop 3
	global_load_dword v1, v0, s[4:5] sc1
	s_waitcnt vmcnt(0)
	v_cmp_gt_u32_e32 vcc, v19, v1
	s_and_saveexec_b64 s[28:29], vcc
	s_cbranch_execz .LBB0_53
	s_mov_b32 s2, 1
	s_mov_b64 s[34:35], 0
	s_branch .LBB0_44

.LBB0_48:
	v_readlane_b32 s4, v247, 48
	v_readlane_b32 s5, v247, 49
	s_add_i32 s2, s2, 1
	s_mov_b64 s[40:41], -1
	s_nop 2
	global_load_dword v1, v0, s[4:5] sc1
	s_waitcnt vmcnt(0)
	v_cmp_le_u32_e32 vcc, v19, v1
	s_orn2_b64 s[38:39], vcc, exec
	s_branch .LBB0_43

.LBB0_57:
	s_or_b64 exec, exec, s[28:29]
	v_cvt_f32_u32_e32 v4, v1
	s_waitcnt vmcnt(0)
	v_readfirstlane_b32 s2, v3
	v_sub_u32_e32 v3, 0, v1
	v_readlane_b32 s4, v247, 50
	v_rcp_iflag_f32_e32 v4, v4
	v_add_u32_e32 v2, s2, v2
	v_add_u32_e32 v5, 1, v2
	v_readlane_b32 s5, v247, 51
	v_mul_f32_e32 v4, 0x4f7ffffe, v4
	v_cvt_u32_f32_e32 v4, v4
	s_mov_b64 s[28:29], -1
	v_mul_lo_u32 v3, v3, v4
	v_mul_hi_u32 v3, v4, v3
	v_add_u32_e32 v3, v4, v3
	v_mul_hi_u32 v3, v2, v3
	v_mul_lo_u32 v4, v3, v1
	v_sub_u32_e32 v2, v2, v4
	v_add_u32_e32 v6, 1, v3
	v_sub_u32_e32 v4, v2, v1
	v_cmp_ge_u32_e32 vcc, v2, v1
	s_nop 1
	v_cndmask_b32_e32 v3, v3, v6, vcc
	v_cndmask_b32_e32 v2, v2, v4, vcc
	v_add_u32_e32 v4, 1, v3
	v_cmp_ge_u32_e32 vcc, v2, v1
	s_nop 1
	v_cndmask_b32_e32 v4, v3, v4, vcc
	v_mul_lo_u32 v2, v1, v4
	v_add_u32_e32 v1, v2, v1
	v_mov_b32_e32 v19, v1
	v_cmp_ne_u32_e32 vcc, v5, v1
	v_mov_b64_e32 v[2:3], s[4:5]
	s_and_saveexec_b64 s[22:23], vcc
	s_cbranch_execz .LBB0_69
	v_readlane_b32 s4, v247, 48
	v_readlane_b32 s5, v247, 49
	s_mov_b64 s[34:35], 0
	s_nop 3
	global_load_dword v1, v0, s[4:5] sc1
	s_waitcnt vmcnt(0)
	v_cmp_gt_u32_e32 vcc, v19, v1
	s_and_saveexec_b64 s[28:29], vcc
	s_cbranch_execz .LBB0_68
	s_mov_b32 s2, 1
	s_branch .LBB0_61
